# attention V tile also staged by LDS-DMA (144B rows, natural key order, ds_read_b64 pairs, no permlane swaps) on top of v40
# baseline (speedup 1.0000x reference)
; #define LAS __attribute__((address_space(3)))
; #define MFMA32(a, b, c) __builtin_amdgcn_mfma_f32_32x32x16_bf16((a), (b), (c), 0, 0, 0)
; DI void attn_phase(ldsp lds, const bf16_t* Q, const bf16_t* KN, const bf16_t* KR, const bf16_t* VT, bf16_t* O, int vcu, int G) {
;     ...
;                 if (key0 <= q0 + 31) {
;                     ldsp Lb = lds + buf * AT_BUF;
;                     f32x16 s0, s1;
; #pragma unroll
;                     for (int r = 0; r < 16; ++r) { s0[r] = 0.f; s1[r] = 0.f; }
;                     ldsp kb = Lb + l31 * AT_KP + hh * 16;
;                     bf16x8 kf[6];
; #pragma unroll
;                     for (int i = 0; i < 6; ++i) kf[i] = *(const LAS bf16x8*)(kb + (i & 1) * 32 * AT_KP + (i >> 1) * 32);
; #pragma unroll
;                     for (int i = 0; i < 24; ++i) { const bf16x8 cur = kf[i % 6];
;                         if (i + 6 < 24) kf[i % 6] = *(const LAS bf16x8*)(kb + ((i + 6) & 1) * 32 * AT_KP + ((i + 6) >> 1) * 32);
;                         if (i & 1) s1 = MFMA32(cur, qf[i >> 1], s1); else s0 = MFMA32(cur, qf[i >> 1], s0); }
;     ...
;                                 const bf16x8 va = lds_8x2(Lb + AT_VOFF + (d * 32 + l31) * AT_VP + (kb2 * 32 + 16 * s2 + 4 * hh) * 2, 16);
.LBB0_1454:
	s_mul_i32 s28, s27, 0xac00
	s_add_i32 s28, s28, 0
	v_add3_u32 v1, s28, v171, v170
	ds_read_b128 v[66:69], v1 offset:12800
	ds_read_b128 v[70:73], v1
	ds_read_b128 v[230:233], v1 offset:32
	ds_read_b128 v[234:237], v1 offset:12832
	ds_read_b128 v[238:241], v1 offset:64
	ds_read_b128 v[242:245], v1 offset:12864
	s_add_i32 s29, s6, 63
	s_cmp_le_i32 s29, s14
	s_waitcnt lgkmcnt(4)
	v_mfma_f32_32x32x16_bf16 v[82:97], v[70:73], v[98:101], 0
	ds_read_b128 v[246:249], v1 offset:96
	v_mfma_f32_32x32x16_bf16 v[66:81], v[66:69], v[98:101], 0
	ds_read_b128 v[250:253], v1 offset:12896
	s_waitcnt lgkmcnt(5)
	v_mfma_f32_32x32x16_bf16 v[82:97], v[230:233], v[102:105], v[82:97]
	ds_read_b128 v[230:233], v1 offset:128
	s_waitcnt lgkmcnt(5)
	v_mfma_f32_32x32x16_bf16 v[66:81], v[234:237], v[102:105], v[66:81]
	ds_read_b128 v[234:237], v1 offset:12928
	s_waitcnt lgkmcnt(5)
	v_mfma_f32_32x32x16_bf16 v[82:97], v[238:241], v[110:113], v[82:97]
	ds_read_b128 v[238:241], v1 offset:160
	s_waitcnt lgkmcnt(5)
	v_mfma_f32_32x32x16_bf16 v[66:81], v[242:245], v[110:113], v[66:81]
	ds_read_b128 v[242:245], v1 offset:12960
	s_waitcnt lgkmcnt(5)
	v_mfma_f32_32x32x16_bf16 v[82:97], v[246:249], v[114:117], v[82:97]
	ds_read_b128 v[246:249], v1 offset:192
	s_waitcnt lgkmcnt(5)
	v_mfma_f32_32x32x16_bf16 v[66:81], v[250:253], v[114:117], v[66:81]
	ds_read_b128 v[250:253], v1 offset:12992
	s_waitcnt lgkmcnt(5)
	v_mfma_f32_32x32x16_bf16 v[82:97], v[230:233], v[122:125], v[82:97]
	ds_read_b128 v[230:233], v1 offset:224
	s_waitcnt lgkmcnt(5)
	v_mfma_f32_32x32x16_bf16 v[66:81], v[234:237], v[122:125], v[66:81]
	ds_read_b128 v[234:237], v1 offset:13024
	s_waitcnt lgkmcnt(5)
	v_mfma_f32_32x32x16_bf16 v[82:97], v[238:241], v[126:129], v[82:97]
	ds_read_b128 v[238:241], v1 offset:256
	s_waitcnt lgkmcnt(5)
	v_mfma_f32_32x32x16_bf16 v[66:81], v[242:245], v[126:129], v[66:81]
	ds_read_b128 v[242:245], v1 offset:13056
	s_waitcnt lgkmcnt(5)
	v_mfma_f32_32x32x16_bf16 v[82:97], v[246:249], v[130:133], v[82:97]
	ds_read_b128 v[246:249], v1 offset:288
	s_waitcnt lgkmcnt(5)
	v_mfma_f32_32x32x16_bf16 v[66:81], v[250:253], v[130:133], v[66:81]
	ds_read_b128 v[250:253], v1 offset:13088
	s_waitcnt lgkmcnt(5)
	v_mfma_f32_32x32x16_bf16 v[82:97], v[230:233], v[138:141], v[82:97]
	ds_read_b128 v[230:233], v1 offset:320
	s_waitcnt lgkmcnt(5)
	v_mfma_f32_32x32x16_bf16 v[66:81], v[234:237], v[138:141], v[66:81]
	ds_read_b128 v[234:237], v1 offset:13120
	s_waitcnt lgkmcnt(5)
	v_mfma_f32_32x32x16_bf16 v[82:97], v[238:241], v[142:145], v[82:97]
	ds_read_b128 v[238:241], v1 offset:352
	s_waitcnt lgkmcnt(5)
	v_mfma_f32_32x32x16_bf16 v[66:81], v[242:245], v[142:145], v[66:81]
	ds_read_b128 v[242:245], v1 offset:13152
	s_waitcnt lgkmcnt(5)
	v_mfma_f32_32x32x16_bf16 v[82:97], v[246:249], v[146:149], v[82:97]
	s_waitcnt lgkmcnt(4)
	v_mfma_f32_32x32x16_bf16 v[66:81], v[250:253], v[146:149], v[66:81]
	s_waitcnt lgkmcnt(3)
	v_mfma_f32_32x32x16_bf16 v[82:97], v[230:233], v[150:153], v[82:97]
	s_waitcnt lgkmcnt(2)
	v_mfma_f32_32x32x16_bf16 v[66:81], v[234:237], v[150:153], v[66:81]
	s_waitcnt lgkmcnt(1)
	v_mfma_f32_32x32x16_bf16 v[82:97], v[238:241], v[154:157], v[82:97]
	s_waitcnt lgkmcnt(0)
	v_mfma_f32_32x32x16_bf16 v[66:81], v[242:245], v[154:157], v[66:81]
	v_add3_u32 v253, s28, v168, v169
	ds_read_b64 v[232:233], v253 offset:25600
	ds_read_b64 v[234:235], v253 offset:25616
	ds_read_b64 v[236:237], v253 offset:30208
	ds_read_b64 v[238:239], v253 offset:30224
	ds_read_b64 v[240:241], v253 offset:34816
	ds_read_b64 v[242:243], v253 offset:34832
	ds_read_b64 v[244:245], v253 offset:39424
	ds_read_b64 v[246:247], v253 offset:39440
	ds_read_b64 v[248:249], v253 offset:25632
	ds_read_b64 v[250:251], v253 offset:25648
	s_cbranch_scc1 .LBB0_1456
; DI int crow(int reg, int hh) { return (reg & 3) + 8 * (reg >> 2) + 4 * hh; }
; DI void attn_phase(ldsp lds, const bf16_t* Q, const bf16_t* KN, const bf16_t* KR, const bf16_t* VT, bf16_t* O, int vcu, int G) {
;     ...
;                     if (key0 + 63 > q0) {
;                         const int qpos = q0 + l31;
; #pragma unroll
;                         for (int r = 0; r < 16; ++r) { const int key = key0 + crow(r, hh); if (key > qpos) s0[r] = -1e30f; if (key + 32 > qpos) s1[r] = -1e30f; }
;                     }
	v_add_u32_e32 v1, s6, v183
	v_add_u32_e32 v230, 32, v1
	v_cmp_le_i32_e32 vcc, v230, v228
	v_add_u32_e32 v230, 33, v1
	s_nop 6
	v_cndmask_b32_e32 v66, v226, v66, vcc
	v_cmp_lt_i32_e32 vcc, v1, v228
	s_nop 1
	v_cndmask_b32_e32 v83, v226, v83, vcc
	v_cmp_le_i32_e32 vcc, v1, v228
	s_nop 1
	v_cndmask_b32_e32 v82, v226, v82, vcc
	v_cmp_le_i32_e32 vcc, v230, v228
	v_add_u32_e32 v230, 2, v1
	s_nop 0
	v_cndmask_b32_e32 v67, v226, v67, vcc
	v_cmp_le_i32_e32 vcc, v230, v228
	v_add_u32_e32 v230, 34, v1
	s_nop 0
	v_cndmask_b32_e32 v84, v226, v84, vcc
	v_cmp_le_i32_e32 vcc, v230, v228
	v_add_u32_e32 v230, 3, v1
	s_nop 0
	v_cndmask_b32_e32 v68, v226, v68, vcc
	v_cmp_le_i32_e32 vcc, v230, v228
	v_add_u32_e32 v230, 35, v1
	s_nop 0
	v_cndmask_b32_e32 v85, v226, v85, vcc
	v_cmp_le_i32_e32 vcc, v230, v228
	v_add_u32_e32 v230, 8, v1
	s_nop 0
	v_cndmask_b32_e32 v69, v226, v69, vcc
	v_cmp_le_i32_e32 vcc, v230, v228
	v_add_u32_e32 v230, 40, v1
	s_nop 0
	v_cndmask_b32_e32 v86, v226, v86, vcc
	v_cmp_le_i32_e32 vcc, v230, v228
	v_add_u32_e32 v230, 9, v1
	s_nop 0
	v_cndmask_b32_e32 v70, v226, v70, vcc
	v_cmp_le_i32_e32 vcc, v230, v228
	v_add_u32_e32 v230, 41, v1
	s_nop 0
	v_cndmask_b32_e32 v87, v226, v87, vcc
	v_cmp_le_i32_e32 vcc, v230, v228
	v_add_u32_e32 v230, 10, v1
	s_nop 0
	v_cndmask_b32_e32 v71, v226, v71, vcc
	v_cmp_le_i32_e32 vcc, v230, v228
	v_add_u32_e32 v230, 42, v1
	s_nop 0
	v_cndmask_b32_e32 v88, v226, v88, vcc
	v_cmp_le_i32_e32 vcc, v230, v228
	v_add_u32_e32 v230, 11, v1
	s_nop 0
	v_cndmask_b32_e32 v72, v226, v72, vcc
	v_cmp_le_i32_e32 vcc, v230, v228
	v_add_u32_e32 v230, 43, v1
	s_nop 0
	v_cndmask_b32_e32 v89, v226, v89, vcc
	v_cmp_le_i32_e32 vcc, v230, v228
	v_add_u32_e32 v230, 16, v1
	s_nop 0
	v_cndmask_b32_e32 v73, v226, v73, vcc
	v_cmp_le_i32_e32 vcc, v230, v228
	v_add_u32_e32 v230, 48, v1
	s_nop 0
	v_cndmask_b32_e32 v90, v226, v90, vcc
	v_cmp_le_i32_e32 vcc, v230, v228
	v_add_u32_e32 v230, 17, v1
	s_nop 0
	v_cndmask_b32_e32 v74, v226, v74, vcc
	v_cmp_le_i32_e32 vcc, v230, v228
	v_add_u32_e32 v230, 49, v1
	s_nop 0
	v_cndmask_b32_e32 v91, v226, v91, vcc
	v_cmp_le_i32_e32 vcc, v230, v228
	v_add_u32_e32 v230, 18, v1
	s_nop 0
	v_cndmask_b32_e32 v75, v226, v75, vcc
	v_cmp_le_i32_e32 vcc, v230, v228
	v_add_u32_e32 v230, 50, v1
	s_nop 0
	v_cndmask_b32_e32 v92, v226, v92, vcc
	v_cmp_le_i32_e32 vcc, v230, v228
	v_add_u32_e32 v230, 19, v1
	s_nop 0
	v_cndmask_b32_e32 v76, v226, v76, vcc
	v_cmp_le_i32_e32 vcc, v230, v228
	v_add_u32_e32 v230, 51, v1
	s_nop 0
	v_cndmask_b32_e32 v93, v226, v93, vcc
	v_cmp_le_i32_e32 vcc, v230, v228
	v_add_u32_e32 v230, 24, v1
	s_nop 0
	v_cndmask_b32_e32 v77, v226, v77, vcc
	v_cmp_le_i32_e32 vcc, v230, v228
	v_add_u32_e32 v230, 56, v1
	s_nop 0
	v_cndmask_b32_e32 v94, v226, v94, vcc
	v_cmp_le_i32_e32 vcc, v230, v228
	v_add_u32_e32 v230, 25, v1
	s_nop 0
	v_cndmask_b32_e32 v78, v226, v78, vcc
	v_cmp_le_i32_e32 vcc, v230, v228
	v_add_u32_e32 v230, 57, v1
	s_nop 0
	v_cndmask_b32_e32 v95, v226, v95, vcc
	v_cmp_le_i32_e32 vcc, v230, v228
	v_add_u32_e32 v230, 26, v1
	s_nop 0
	v_cndmask_b32_e32 v79, v226, v79, vcc
	v_cmp_le_i32_e32 vcc, v230, v228
	v_add_u32_e32 v230, 58, v1
	s_nop 0
	v_cndmask_b32_e32 v96, v226, v96, vcc
	v_cmp_le_i32_e32 vcc, v230, v228
	v_add_u32_e32 v230, 27, v1
	v_add_u32_e32 v1, 59, v1
	v_cndmask_b32_e32 v80, v226, v80, vcc
	v_cmp_le_i32_e32 vcc, v230, v228
	s_nop 1
	v_cndmask_b32_e32 v97, v226, v97, vcc
	v_cmp_le_i32_e32 vcc, v1, v228
	s_nop 1
	v_cndmask_b32_e32 v81, v226, v81, vcc

; #define MFMA32(a, b, c) __builtin_amdgcn_mfma_f32_32x32x16_bf16((a), (b), (c), 0, 0, 0)
; DI void attn_phase(ldsp lds, const bf16_t* Q, const bf16_t* KN, const bf16_t* KR, const bf16_t* VT, bf16_t* O, int vcu, int G) {
;     ...
;                     float rs = 0.f;
; #pragma unroll
;                     for (int r = 0; r < 16; ++r) { s0[r] = __builtin_amdgcn_exp2f(s0[r] - mrun); s1[r] = __builtin_amdgcn_exp2f(s1[r] - mrun); rs += s0[r] + s1[r]; }
;                     lrun += rs;
;                     bf16x8 pa[2][2];
;                     pa[0][0] = pack8(s0, 0); pa[0][1] = pack8(s0, 1); pa[1][0] = pack8(s1, 0); pa[1][1] = pack8(s1, 1);
; #pragma unroll
;                     for (int kb2 = 0; kb2 < 2; ++kb2)
; #pragma unroll
;                         for (int s2 = 0; s2 < 2; ++s2)
; #pragma unroll
;                             for (int d = 0; d < 4; ++d) {
;                                 const bf16x8 va = lds_8x2(Lb + AT_VOFF + (d * 32 + l31) * AT_VP + (kb2 * 32 + 16 * s2 + 4 * hh) * 2, 16);
;                                 o[d] = MFMA32(va, pa[kb2][s2], o[d]); }
.LBB0_1458:
	s_sleep 8
	v_sub_f32_e32 v82, v82, v229
	v_sub_f32_e32 v83, v83, v229
	v_sub_f32_e32 v84, v84, v229
	v_sub_f32_e32 v85, v85, v229
	v_sub_f32_e32 v86, v86, v229
	v_sub_f32_e32 v87, v87, v229
	v_sub_f32_e32 v88, v88, v229
	v_sub_f32_e32 v89, v89, v229
	v_exp_f32_e32 v82, v82
	v_exp_f32_e32 v83, v83
	v_exp_f32_e32 v84, v84
	v_exp_f32_e32 v85, v85
	v_exp_f32_e32 v86, v86
	v_exp_f32_e32 v87, v87
	v_exp_f32_e32 v88, v88
	v_exp_f32_e32 v89, v89
	v_add_f32_e32 v1, v82, v84
	v_add_f32_e32 v230, v83, v85
	v_add_f32_e32 v1, v1, v86
	v_add_f32_e32 v230, v230, v87
	v_add_f32_e32 v1, v1, v88
	v_add_f32_e32 v230, v230, v89
	v_cvt_pk_bf16_f32 v82, v82, v83
	v_cvt_pk_bf16_f32 v83, v84, v85
	v_cvt_pk_bf16_f32 v84, v86, v87
	v_cvt_pk_bf16_f32 v85, v88, v89
	s_nop 1
	s_waitcnt lgkmcnt(8)
	v_mfma_f32_32x32x16_bf16 v[50:65], v[232:235], v[82:85], v[50:65]
	ds_read_b64 v[232:233], v253 offset:30240
	ds_read_b64 v[234:235], v253 offset:30256
	v_sub_f32_e32 v90, v90, v229
	v_sub_f32_e32 v91, v91, v229
	v_sub_f32_e32 v92, v92, v229
	v_sub_f32_e32 v93, v93, v229
	v_sub_f32_e32 v94, v94, v229
	v_sub_f32_e32 v95, v95, v229
	v_sub_f32_e32 v96, v96, v229
	s_waitcnt lgkmcnt(8)
	v_mfma_f32_32x32x16_bf16 v[34:49], v[236:239], v[82:85], v[34:49]
	ds_read_b64 v[236:237], v253 offset:34848
	ds_read_b64 v[238:239], v253 offset:34864
	v_sub_f32_e32 v97, v97, v229
	v_exp_f32_e32 v90, v90
	v_exp_f32_e32 v91, v91
	v_exp_f32_e32 v92, v92
	v_exp_f32_e32 v93, v93
	v_exp_f32_e32 v94, v94
	v_exp_f32_e32 v95, v95
	s_waitcnt lgkmcnt(8)
	v_mfma_f32_32x32x16_bf16 v[18:33], v[240:243], v[82:85], v[18:33]
	ds_read_b64 v[240:241], v253 offset:39456
	ds_read_b64 v[242:243], v253 offset:39472
	v_exp_f32_e32 v96, v96
	v_exp_f32_e32 v97, v97
	v_add_f32_e32 v1, v1, v90
	v_add_f32_e32 v230, v230, v91
	v_add_f32_e32 v1, v1, v92
	v_add_f32_e32 v230, v230, v93
	v_add_f32_e32 v1, v1, v94
	s_waitcnt lgkmcnt(8)
	v_mfma_f32_32x32x16_bf16 v[2:17], v[244:247], v[82:85], v[2:17]
	ds_read_b64 v[244:245], v253 offset:25664
	ds_read_b64 v[246:247], v253 offset:25680
	v_add_f32_e32 v230, v230, v95
	v_add_f32_e32 v1, v1, v96
	v_add_f32_e32 v230, v230, v97
	v_cvt_pk_bf16_f32 v90, v90, v91
	v_cvt_pk_bf16_f32 v91, v92, v93
	v_cvt_pk_bf16_f32 v92, v94, v95
	v_cvt_pk_bf16_f32 v93, v96, v97
	s_nop 1
	s_waitcnt lgkmcnt(8)
	v_mfma_f32_32x32x16_bf16 v[50:65], v[248:251], v[90:93], v[50:65]
	ds_read_b64 v[248:249], v253 offset:30272
	ds_read_b64 v[250:251], v253 offset:30288
	v_sub_f32_e32 v66, v66, v229
	v_sub_f32_e32 v67, v67, v229
	v_sub_f32_e32 v68, v68, v229
	v_sub_f32_e32 v69, v69, v229
	v_sub_f32_e32 v70, v70, v229
	v_sub_f32_e32 v71, v71, v229
	v_sub_f32_e32 v72, v72, v229
	s_waitcnt lgkmcnt(8)
	v_mfma_f32_32x32x16_bf16 v[34:49], v[232:235], v[90:93], v[34:49]
	ds_read_b64 v[232:233], v253 offset:34880
	ds_read_b64 v[234:235], v253 offset:34896
	v_sub_f32_e32 v73, v73, v229
	v_exp_f32_e32 v66, v66
	v_exp_f32_e32 v67, v67
	v_exp_f32_e32 v68, v68
	v_exp_f32_e32 v69, v69
	v_exp_f32_e32 v70, v70
	v_exp_f32_e32 v71, v71
	s_waitcnt lgkmcnt(8)
	v_mfma_f32_32x32x16_bf16 v[18:33], v[236:239], v[90:93], v[18:33]
	ds_read_b64 v[236:237], v253 offset:39488
	ds_read_b64 v[238:239], v253 offset:39504
	v_exp_f32_e32 v72, v72
	v_exp_f32_e32 v73, v73
	v_add_f32_e32 v1, v1, v66
	v_add_f32_e32 v230, v230, v67
	v_add_f32_e32 v1, v1, v68
	v_add_f32_e32 v230, v230, v69
	v_add_f32_e32 v1, v1, v70
	s_waitcnt lgkmcnt(8)
	v_mfma_f32_32x32x16_bf16 v[2:17], v[240:243], v[90:93], v[2:17]
	ds_read_b64 v[240:241], v253 offset:25696
	ds_read_b64 v[242:243], v253 offset:25712
	v_add_f32_e32 v230, v230, v71
	v_add_f32_e32 v1, v1, v72
	v_add_f32_e32 v230, v230, v73
	v_cvt_pk_bf16_f32 v66, v66, v67
	v_cvt_pk_bf16_f32 v67, v68, v69
	v_cvt_pk_bf16_f32 v68, v70, v71
	v_cvt_pk_bf16_f32 v69, v72, v73
	s_nop 1
	s_waitcnt lgkmcnt(8)
	v_mfma_f32_32x32x16_bf16 v[50:65], v[244:247], v[66:69], v[50:65]
	ds_read_b64 v[244:245], v253 offset:30304
	ds_read_b64 v[246:247], v253 offset:30320
	v_sub_f32_e32 v74, v74, v229
	v_sub_f32_e32 v75, v75, v229
	v_sub_f32_e32 v76, v76, v229
	v_sub_f32_e32 v77, v77, v229
	v_sub_f32_e32 v78, v78, v229
	v_sub_f32_e32 v79, v79, v229
	v_sub_f32_e32 v80, v80, v229
	s_waitcnt lgkmcnt(8)
	v_mfma_f32_32x32x16_bf16 v[34:49], v[248:251], v[66:69], v[34:49]
	ds_read_b64 v[248:249], v253 offset:34912
	ds_read_b64 v[250:251], v253 offset:34928
	v_sub_f32_e32 v81, v81, v229
	v_exp_f32_e32 v74, v74
	v_exp_f32_e32 v75, v75
	v_exp_f32_e32 v76, v76
	v_exp_f32_e32 v77, v77
	v_exp_f32_e32 v78, v78
	v_exp_f32_e32 v79, v79
	s_waitcnt lgkmcnt(8)
	v_mfma_f32_32x32x16_bf16 v[18:33], v[232:235], v[66:69], v[18:33]
	ds_read_b64 v[232:233], v253 offset:39520
	ds_read_b64 v[234:235], v253 offset:39536
	v_exp_f32_e32 v80, v80
	v_exp_f32_e32 v81, v81
	v_add_f32_e32 v1, v1, v74
	v_add_f32_e32 v230, v230, v75
	v_add_f32_e32 v1, v1, v76
	v_add_f32_e32 v230, v230, v77
	v_add_f32_e32 v1, v1, v78
	s_waitcnt lgkmcnt(8)
	v_mfma_f32_32x32x16_bf16 v[2:17], v[236:239], v[66:69], v[2:17]
	v_add_f32_e32 v230, v230, v79
	v_add_f32_e32 v1, v1, v80
	v_add_f32_e32 v230, v230, v81
	v_cvt_pk_bf16_f32 v74, v74, v75
	v_cvt_pk_bf16_f32 v75, v76, v77
	v_cvt_pk_bf16_f32 v76, v78, v79
	v_cvt_pk_bf16_f32 v77, v80, v81
	s_nop 1
	s_waitcnt lgkmcnt(6)
	v_mfma_f32_32x32x16_bf16 v[50:65], v[240:243], v[74:77], v[50:65]
	s_waitcnt lgkmcnt(4)
	v_mfma_f32_32x32x16_bf16 v[34:49], v[244:247], v[74:77], v[34:49]
	s_waitcnt lgkmcnt(2)
	v_mfma_f32_32x32x16_bf16 v[18:33], v[248:251], v[74:77], v[18:33]
	s_waitcnt lgkmcnt(0)
	v_mfma_f32_32x32x16_bf16 v[2:17], v[232:235], v[74:77], v[2:17]
	v_add_f32_e32 v1, v1, v230
	v_add_f32_e32 v227, v227, v1
	s_andn2_b64 vcc, exec, s[16:17]
	s_cbranch_vccnz .LBB0_1449
